# S5 sample part: the 16 initial-state loads hoisted to the top (no per-chain vmcnt drain)
# baseline (speedup 1.0000x reference)
.LBB0_695:
	s_lshl_b32 s20, s51, 3
	s_add_i32 s20, s20, s88
	s_lshl_b32 s24, s20, 5
	s_addk_i32 s24, 0x2000
	v_or_b32_e32 v2, s24, v170
	v_mov_b32_e32 v3, v173
	v_lshlrev_b64 v[2:3], 11, v[2:3]
	v_lshl_add_u64 v[2:3], s[30:31], 0, v[2:3]
	v_lshl_add_u64 v[2:3], s[22:23], 1, v[2:3]
	v_lshl_add_u64 v[2:3], v[2:3], 0, v[172:173]
	global_load_dwordx4 v[50:53], v[2:3], off
	v_lshl_or_b32 v2, s20, 9, v217
	v_add_u32_e32 v40, s50, v2
	v_ashrrev_i32_e32 v41, 31, v40
	v_lshlrev_b32_e32 v48, 2, v170
	v_lshlrev_b64 v[34:35], 8, v[40:41]
	v_readlane_b32 s4, v251, 6
	v_or_b32_e32 v2, v34, v48
	v_mov_b32_e32 v3, v35
	v_readlane_b32 s16, v251, 18
	v_readlane_b32 s17, v251, 19
	v_readlane_b32 s14, v251, 16
	v_readlane_b32 s15, v251, 17
	v_lshl_add_u64 v[38:39], s[16:17], 0, v[2:3]
	v_readlane_b32 s80, v251, 44
	v_lshl_add_u64 v[36:37], s[14:15], 0, v[2:3]
	global_load_dword v41, v[38:39], off
	global_load_dword v49, v[36:37], off
	v_readlane_b32 s81, v251, 45
	v_add_u32_e32 v4, 0x80, v40
	v_ashrrev_i32_e32 v5, 31, v4
	v_lshl_add_u64 v[2:3], s[80:81], 0, v[2:3]
	v_add_co_u32_e32 v44, vcc, s78, v2
	v_lshlrev_b64 v[54:55], 8, v[4:5]
	s_nop 0
	v_addc_co_u32_e32 v45, vcc, 0, v3, vcc
	v_add_co_u32_e32 v46, vcc, s79, v2
	v_or_b32_e32 v42, v54, v48
	s_nop 0
	v_addc_co_u32_e32 v47, vcc, 0, v3, vcc
	v_mov_b32_e32 v43, v55
	v_lshl_add_u64 v[58:59], s[16:17], 0, v[42:43]
	v_lshl_add_u64 v[56:57], s[14:15], 0, v[42:43]
	global_load_dword v232, v[58:59], off
	global_load_dword v233, v[56:57], off
	global_load_dword v238, v[38:39], off offset:128
	global_load_dword v239, v[36:37], off offset:128
	global_load_dword v240, v[58:59], off offset:128
	global_load_dword v241, v[56:57], off offset:128
	v_add_u32_e32 v246, 0x100, v40
	v_ashrrev_i32_e32 v247, 31, v246
	v_lshlrev_b64 v[246:247], 8, v[246:247]
	v_or_b32_e32 v246, v246, v48
	v_lshl_add_u64 v[248:249], s[16:17], 0, v[246:247]
	v_lshl_add_u64 v[246:247], s[14:15], 0, v[246:247]
	global_load_dword v234, v[248:249], off
	global_load_dword v235, v[246:247], off
	global_load_dword v242, v[248:249], off offset:128
	global_load_dword v243, v[246:247], off offset:128
	v_add_u32_e32 v246, 0x180, v40
	v_ashrrev_i32_e32 v247, 31, v246
	v_lshlrev_b64 v[246:247], 8, v[246:247]
	v_or_b32_e32 v246, v246, v48
	v_lshl_add_u64 v[248:249], s[16:17], 0, v[246:247]
	v_lshl_add_u64 v[246:247], s[14:15], 0, v[246:247]
	global_load_dword v236, v[248:249], off
	global_load_dword v237, v[246:247], off
	global_load_dword v244, v[248:249], off offset:128
	global_load_dword v245, v[246:247], off offset:128
	v_add_u32_e32 v99, 0x800, v230
	v_add_u32_e32 v100, 0x1000, v230
	v_add_u32_e32 v101, 0x1800, v230
	v_readlane_b32 s5, v251, 7
	v_readlane_b32 s6, v251, 8
	v_readlane_b32 s7, v251, 9
	v_readlane_b32 s8, v251, 10
	v_readlane_b32 s9, v251, 11
	v_readlane_b32 s10, v251, 12
	v_readlane_b32 s11, v251, 13
	v_readlane_b32 s12, v251, 14
	v_readlane_b32 s13, v251, 15
	v_readlane_b32 s18, v251, 20
	v_readlane_b32 s19, v251, 21
	v_readlane_b32 s82, v251, 46
	v_readlane_b32 s83, v251, 47
	v_readlane_b32 s84, v251, 48
	v_readlane_b32 s85, v251, 49
	v_readlane_b32 s86, v251, 50
	v_readlane_b32 s87, v251, 51
	s_waitcnt vmcnt(2)
	v_mfma_f32_32x32x16_bf16 v[18:33], v[50:53], v[154:157], 0
	s_waitcnt vmcnt(1)
	s_nop 10
	v_fma_f32 v64, -v201, v41, v18
	v_mfma_f32_32x32x16_bf16 v[2:17], v[50:53], v[158:161], 0
	s_waitcnt vmcnt(0)
	v_fmac_f32_e32 v64, v231, v49
	s_nop 9
	v_fma_f32 v65, v201, v49, v2
	v_fmac_f32_e32 v65, v231, v41
	v_add_u32_e32 v2, 0x100, v40
	v_fma_f32 v66, -v201, v65, v19
	v_fma_f32 v67, v201, v64, v3
	v_fmac_f32_e32 v66, v231, v64
	v_fmac_f32_e32 v67, v231, v65
	v_ashrrev_i32_e32 v3, 31, v2
	v_fma_f32 v68, -v201, v67, v20
	v_fma_f32 v69, v201, v66, v4
	v_fmac_f32_e32 v68, v231, v66
	v_fmac_f32_e32 v69, v231, v67
	s_nop 0
	v_fma_f32 v70, -v201, v69, v21
	v_fma_f32 v71, v201, v68, v5
	v_fmac_f32_e32 v70, v231, v68
	v_fmac_f32_e32 v71, v231, v69
	global_store_dword v[44:45], v70, off
	global_store_dword v[46:47], v71, off
	v_mov_b32_e32 v41, v232
	s_nop 0
	v_mov_b32_e32 v44, v233
	v_lshlrev_b64 v[4:5], 8, v[2:3]
	v_lshl_add_u64 v[2:3], s[80:81], 0, v[42:43]
	v_add_co_u32_e32 v20, vcc, s78, v2
	v_or_b32_e32 v18, v4, v48
	s_nop 0
	v_addc_co_u32_e32 v21, vcc, 0, v3, vcc
	v_mov_b32_e32 v19, v5
	v_add_co_u32_e32 v2, vcc, s79, v2
	v_lshl_add_u64 v[62:63], s[16:17], 0, v[18:19]
	s_nop 0
	v_addc_co_u32_e32 v3, vcc, 0, v3, vcc
	v_lshl_add_u64 v[60:61], s[14:15], 0, v[18:19]
	v_lshl_add_u64 v[18:19], s[80:81], 0, v[18:19]
	v_lshl_add_u64 v[4:5], v[192:193], 0, v[4:5]
	s_nop 0
	v_fma_f32 v72, -v201, v41, v22
	s_nop 0
	v_fma_f32 v73, v201, v44, v6
	v_fmac_f32_e32 v72, v231, v44
	v_fmac_f32_e32 v73, v231, v41
	v_add_co_u32_e32 v22, vcc, s78, v18
	v_fma_f32 v74, -v201, v73, v23
	v_fma_f32 v75, v201, v72, v7
	v_fmac_f32_e32 v74, v231, v72
	v_fmac_f32_e32 v75, v231, v73
	v_addc_co_u32_e32 v23, vcc, 0, v19, vcc
	v_fma_f32 v76, -v201, v75, v24
	v_fma_f32 v77, v201, v74, v8
	v_fmac_f32_e32 v76, v231, v74
	v_fmac_f32_e32 v77, v231, v75
	v_add_co_u32_e32 v18, vcc, s79, v18
	v_fma_f32 v78, -v201, v77, v25
	v_fma_f32 v79, v201, v76, v9
	v_fmac_f32_e32 v78, v231, v76
	v_fmac_f32_e32 v79, v231, v77
	global_store_dword v[20:21], v78, off
	global_store_dword v[2:3], v79, off
	v_mov_b32_e32 v24, v234
	v_mov_b32_e32 v25, v235
	v_add_u32_e32 v2, 0x180, v40
	v_ashrrev_i32_e32 v3, 31, v2
	v_lshlrev_b64 v[2:3], 8, v[2:3]
	v_or_b32_e32 v20, v2, v48
	v_mov_b32_e32 v21, v3
	v_lshl_add_u64 v[8:9], s[16:17], 0, v[20:21]
	v_addc_co_u32_e32 v19, vcc, 0, v19, vcc
	v_lshl_add_u64 v[6:7], s[14:15], 0, v[20:21]
	v_lshl_add_u64 v[2:3], v[192:193], 0, v[2:3]
	s_nop 0
	v_fma_f32 v80, -v201, v24, v26
	s_nop 0
	v_fma_f32 v81, v201, v25, v10
	v_fmac_f32_e32 v80, v231, v25
	v_fmac_f32_e32 v81, v231, v24
	s_nop 0
	v_fma_f32 v82, -v201, v81, v27
	v_fma_f32 v83, v201, v80, v11
	v_fmac_f32_e32 v82, v231, v80
	v_fmac_f32_e32 v83, v231, v81
	v_lshl_add_u64 v[10:11], s[80:81], 0, v[20:21]
	v_fma_f32 v84, -v201, v83, v28
	v_fma_f32 v85, v201, v82, v12
	v_fmac_f32_e32 v84, v231, v82
	v_fmac_f32_e32 v85, v231, v83
	v_add_co_u32_e32 v12, vcc, s78, v10
	v_fma_f32 v86, -v201, v85, v29
	v_fma_f32 v87, v201, v84, v13
	v_fmac_f32_e32 v86, v231, v84
	v_fmac_f32_e32 v87, v231, v85
	global_store_dword v[22:23], v86, off
	global_store_dword v[18:19], v87, off
	v_mov_b32_e32 v18, v236
	s_nop 0
	v_mov_b32_e32 v19, v237
	v_addc_co_u32_e32 v13, vcc, 0, v11, vcc
	v_add_co_u32_e32 v10, vcc, s79, v10
	s_nop 0
	v_fma_f32 v88, -v201, v18, v30
	s_nop 0
	v_fma_f32 v89, v201, v19, v14
	v_fmac_f32_e32 v88, v231, v19
	v_fmac_f32_e32 v89, v231, v18
	v_addc_co_u32_e32 v11, vcc, 0, v11, vcc
	v_fma_f32 v90, -v201, v89, v31
	v_fma_f32 v91, v201, v88, v15
	v_fmac_f32_e32 v90, v231, v88
	v_fmac_f32_e32 v91, v231, v89
	s_nop 0
	v_fma_f32 v92, -v201, v91, v32
	v_fma_f32 v93, v201, v90, v16
	v_fmac_f32_e32 v92, v231, v90
	v_fmac_f32_e32 v93, v231, v91
	v_cvt_pk_bf16_f32 v16, v89, v91
	v_fma_f32 v94, -v201, v93, v33
	v_fmac_f32_e32 v17, v201, v92
	v_fmac_f32_e32 v94, v231, v92
	v_fmac_f32_e32 v17, v231, v93
	global_store_dword v[12:13], v94, off
	global_store_dword v[10:11], v17, off
	v_mov_b32_e32 v14, v238
	v_mov_b32_e32 v15, v239
	v_lshl_add_u64 v[10:11], v[192:193], 0, v[34:35]
	v_mfma_f32_32x32x16_bf16 v[34:49], v[50:53], v[146:149], 0
	v_add_co_u32_e32 v12, vcc, s78, v10
	v_cvt_pk_bf16_f32 v17, v93, v17
	s_nop 0
	v_addc_co_u32_e32 v13, vcc, 0, v11, vcc
	v_add_co_u32_e32 v10, vcc, s79, v10
	v_mfma_f32_32x32x16_bf16 v[18:33], v[50:53], v[150:153], 0
	s_nop 0
	v_addc_co_u32_e32 v11, vcc, 0, v11, vcc
	s_nop 0
	s_nop 2
	v_fma_f32 v34, -v196, v14, v34
	s_nop 0
	s_nop 3
	v_fma_f32 v95, v196, v15, v18
	v_fmac_f32_e32 v34, v200, v15
	v_fmac_f32_e32 v95, v200, v14
	v_cvt_pk_bf16_f32 v18, v81, v83
	v_fma_f32 v35, -v196, v95, v35
	v_fma_f32 v96, v196, v34, v19
	v_fmac_f32_e32 v35, v200, v34
	v_fmac_f32_e32 v96, v200, v95
	v_cvt_pk_bf16_f32 v19, v85, v87
	v_fma_f32 v36, -v196, v96, v36
	v_fma_f32 v97, v196, v35, v20
	v_fmac_f32_e32 v36, v200, v35
	v_fmac_f32_e32 v97, v200, v96
	v_cvt_pk_bf16_f32 v20, v88, v90
	v_fma_f32 v37, -v196, v97, v37
	v_fma_f32 v98, v196, v36, v21
	v_fmac_f32_e32 v37, v200, v36
	v_fmac_f32_e32 v98, v200, v97
	global_store_dword v[12:13], v37, off offset:128
	global_store_dword v[10:11], v98, off offset:128
	v_mov_b32_e32 v14, v240
	v_mov_b32_e32 v15, v241
	v_lshl_add_u64 v[10:11], v[192:193], 0, v[54:55]
	v_add_co_u32_e32 v12, vcc, s78, v10
	v_cvt_pk_bf16_f32 v21, v92, v94
	s_nop 0
	v_addc_co_u32_e32 v13, vcc, 0, v11, vcc
	v_add_co_u32_e32 v10, vcc, s79, v10
	s_nop 0
	v_fma_f32 v38, -v196, v14, v38
	s_nop 0
	v_fma_f32 v54, v196, v15, v22
	v_fmac_f32_e32 v38, v200, v15
	v_fmac_f32_e32 v54, v200, v14
	v_addc_co_u32_e32 v11, vcc, 0, v11, vcc
	v_fma_f32 v39, -v196, v54, v39
	v_fma_f32 v55, v196, v38, v23
	v_fmac_f32_e32 v39, v200, v38
	v_fmac_f32_e32 v55, v200, v54
	v_cvt_pk_bf16_f32 v22, v34, v35
	v_fma_f32 v40, -v196, v55, v40
	v_fma_f32 v56, v196, v39, v24
	v_fmac_f32_e32 v40, v200, v39
	v_fmac_f32_e32 v56, v200, v55
	v_cvt_pk_bf16_f32 v14, v80, v82
	v_fma_f32 v41, -v196, v56, v41
	v_fma_f32 v57, v196, v40, v25
	v_fmac_f32_e32 v41, v200, v40
	v_fmac_f32_e32 v57, v200, v56
	global_store_dword v[12:13], v41, off offset:128
	global_store_dword v[10:11], v57, off offset:128
	v_mov_b32_e32 v12, v242
	s_nop 0
	v_mov_b32_e32 v13, v243
	v_add_co_u32_e32 v10, vcc, s78, v4
	v_cvt_pk_bf16_f32 v15, v84, v86
	s_nop 0
	v_addc_co_u32_e32 v11, vcc, 0, v5, vcc
	v_add_co_u32_e32 v4, vcc, s79, v4
	v_cvt_pk_bf16_f32 v24, v95, v96
	s_nop 0
	v_addc_co_u32_e32 v5, vcc, 0, v5, vcc
	v_cvt_pk_bf16_f32 v23, v36, v37
	v_cvt_pk_bf16_f32 v25, v97, v98
	s_nop 0
	v_fma_f32 v42, -v196, v12, v42
	s_nop 0
	v_fma_f32 v58, v196, v13, v26
	v_fmac_f32_e32 v42, v200, v13
	v_fmac_f32_e32 v58, v200, v12
	v_cvt_pk_bf16_f32 v26, v38, v39
	v_fma_f32 v43, -v196, v58, v43
	v_fma_f32 v59, v196, v42, v27
	v_fmac_f32_e32 v43, v200, v42
	v_fmac_f32_e32 v59, v200, v58
	v_cvt_pk_bf16_f32 v27, v40, v41
	v_fma_f32 v44, -v196, v59, v44
	v_fma_f32 v60, v196, v43, v28
	v_fmac_f32_e32 v44, v200, v43
	v_fmac_f32_e32 v60, v200, v59
	v_cvt_pk_bf16_f32 v34, v42, v43
	v_fma_f32 v45, -v196, v60, v45
	v_fma_f32 v61, v196, v44, v29
	v_fmac_f32_e32 v45, v200, v44
	v_fmac_f32_e32 v61, v200, v60
	global_store_dword v[10:11], v45, off offset:128
	global_store_dword v[4:5], v61, off offset:128
	v_mov_b32_e32 v62, v244
	v_mov_b32_e32 v63, v245
	v_add_co_u32_e32 v4, vcc, s78, v2
	v_cvt_pk_bf16_f32 v6, v64, v66
	s_nop 0
	v_addc_co_u32_e32 v5, vcc, 0, v3, vcc
	v_add_co_u32_e32 v2, vcc, s79, v2
	v_cvt_pk_bf16_f32 v7, v68, v70
	v_cvt_pk_bf16_f32 v10, v72, v74
	v_cvt_pk_bf16_f32 v11, v76, v78
	v_addc_co_u32_e32 v3, vcc, 0, v3, vcc
	v_cvt_pk_bf16_f32 v8, v65, v67
	v_cvt_pk_bf16_f32 v9, v69, v71
	v_cvt_pk_bf16_f32 v12, v73, v75
	v_cvt_pk_bf16_f32 v13, v77, v79
	v_cvt_pk_bf16_f32 v28, v54, v55
	v_cvt_pk_bf16_f32 v29, v56, v57
	v_cvt_pk_bf16_f32 v35, v44, v45
	v_cvt_pk_bf16_f32 v36, v58, v59
	v_cvt_pk_bf16_f32 v37, v60, v61
	s_nop 0
	v_fma_f32 v38, -v196, v62, v46
	s_nop 0
	v_fma_f32 v39, v196, v63, v30
	v_fmac_f32_e32 v38, v200, v63
	v_fmac_f32_e32 v39, v200, v62
	s_nop 0
	v_fma_f32 v40, -v196, v39, v47
	v_fma_f32 v31, v196, v38, v31
	v_fmac_f32_e32 v40, v200, v38
	v_fmac_f32_e32 v31, v200, v39
	s_nop 0
	v_fma_f32 v41, -v196, v31, v48
	v_fma_f32 v42, v196, v40, v32
	v_fmac_f32_e32 v41, v200, v40
	v_fmac_f32_e32 v42, v200, v31
	v_cvt_pk_bf16_f32 v32, v39, v31
	v_cvt_pk_bf16_f32 v30, v38, v40
	v_fma_f32 v31, -v196, v42, v49
	v_fmac_f32_e32 v33, v196, v41
	v_fmac_f32_e32 v31, v200, v41
	v_fmac_f32_e32 v33, v200, v42
	ds_write2_b64 v230, v[6:7], v[10:11] offset1:2
	ds_write2_b64 v230, v[14:15], v[20:21] offset0:4 offset1:6
	ds_write2_b64 v99, v[22:23], v[26:27] offset1:2
	ds_write2_b64 v100, v[8:9], v[12:13] offset1:2
	ds_write2_b64 v100, v[18:19], v[16:17] offset0:4 offset1:6
	ds_write2_b64 v101, v[24:25], v[28:29] offset1:2
	global_store_dword v[4:5], v31, off offset:128
	global_store_dword v[2:3], v33, off offset:128
	v_cvt_pk_bf16_f32 v31, v41, v31
	v_cvt_pk_bf16_f32 v33, v42, v33
	ds_write2_b64 v99, v[34:35], v[30:31] offset0:4 offset1:6
	ds_write2_b64 v101, v[36:37], v[32:33] offset0:4 offset1:6
	s_waitcnt lgkmcnt(0)
	ds_read_b64_tr_b16 v[2:3], v215
	ds_read_b64_tr_b16 v[4:5], v215 offset:256
	ds_read_b64_tr_b16 v[26:27], v215 offset:1024
	ds_read_b64_tr_b16 v[28:29], v215 offset:1280
	ds_read_b64_tr_b16 v[22:23], v215 offset:2048
	ds_read_b64_tr_b16 v[24:25], v215 offset:2304
	ds_read_b64_tr_b16 v[18:19], v215 offset:3072
	ds_read_b64_tr_b16 v[20:21], v215 offset:3328
	s_waitcnt lgkmcnt(0)
	ds_read_b128 v[6:9], v207
	ds_read_b128 v[30:33], v207 offset:1024
	s_waitcnt lgkmcnt(1)
	v_mfma_f32_32x32x16_bf16 v[2:17], v[2:5], v[6:9], 0
	s_waitcnt lgkmcnt(0)
	v_mfma_f32_32x32x16_bf16 v[2:17], v[26:29], v[30:33], v[2:17]
	ds_read_b128 v[26:29], v207 offset:2048
	ds_read_b128 v[30:33], v207 offset:3072
	s_waitcnt lgkmcnt(1)
	v_mfma_f32_32x32x16_bf16 v[2:17], v[22:25], v[26:29], v[2:17]
	s_waitcnt lgkmcnt(0)
	v_mfma_f32_32x32x16_bf16 v[2:17], v[18:21], v[30:33], v[2:17]
	ds_read_b64_tr_b16 v[30:31], v216
	ds_read_b64_tr_b16 v[32:33], v216 offset:256
	ds_read_b64_tr_b16 v[26:27], v216 offset:1024
	ds_read_b64_tr_b16 v[28:29], v216 offset:1280
	ds_read_b64_tr_b16 v[22:23], v216 offset:2048
	ds_read_b64_tr_b16 v[24:25], v216 offset:2304
	ds_read_b64_tr_b16 v[18:19], v216 offset:3072
	ds_read_b64_tr_b16 v[20:21], v216 offset:3328
	s_waitcnt lgkmcnt(0)
	ds_read_b128 v[34:37], v207 offset:4096
	ds_read_b128 v[38:41], v207 offset:5120
	s_waitcnt lgkmcnt(1)
	v_mfma_f32_32x32x16_bf16 v[2:17], v[30:33], v[34:37], v[2:17]
	s_waitcnt lgkmcnt(0)
	v_mfma_f32_32x32x16_bf16 v[2:17], v[26:29], v[38:41], v[2:17]
	ds_read_b128 v[26:29], v207 offset:6144
	ds_read_b128 v[30:33], v207 offset:7168
	s_waitcnt lgkmcnt(1)
	v_mfma_f32_32x32x16_bf16 v[2:17], v[22:25], v[26:29], v[2:17]
	s_waitcnt lgkmcnt(0)
	v_mfma_f32_32x32x16_bf16 v[2:17], v[18:21], v[30:33], v[2:17]
	v_mfma_f32_32x32x16_bf16 v[2:17], v[50:53], v[162:165], v[2:17]
	s_and_saveexec_b64 s[20:21], s[2:3]
	s_cbranch_execz .LBB0_639
	s_nop 9
	v_mul_f32_e32 v20, 0x3d372713, v2
	v_mul_f32_e32 v20, v2, v20
	v_fma_f32 v20, v2, v20, v2
	v_mul_f32_e32 v20, 0x3fcc422a, v20
	v_mul_f32_e32 v20, 0xbfb8aa3b, v20
	v_exp_f32_e32 v20, v20
	v_or_b32_e32 v172, s24, v218
	v_lshl_add_u64 v[18:19], s[22:23], 1, v[190:191]
	v_add_f32_e32 v20, 1.0, v20
	v_rcp_f32_e32 v20, v20
	s_nop 0
	v_mul_f32_e32 v2, v2, v20
	v_bfe_u32 v20, v2, 16, 1
	v_add3_u32 v2, v2, v20, s75
	v_lshlrev_b64 v[20:21], 11, v[172:173]
	v_lshl_add_u64 v[20:21], v[18:19], 0, v[20:21]
	global_store_short_d16_hi v[20:21], v2, off
	v_mul_f32_e32 v2, 0x3d372713, v3
	v_mul_f32_e32 v2, v3, v2
	v_fma_f32 v2, v3, v2, v3
	v_mul_f32_e32 v2, 0x3fcc422a, v2
	v_mul_f32_e32 v2, 0xbfb8aa3b, v2
	v_exp_f32_e32 v2, v2
	s_nop 0
	v_add_f32_e32 v2, 1.0, v2
	v_rcp_f32_e32 v2, v2
	s_nop 0
	v_mul_f32_e32 v2, v3, v2
	v_bfe_u32 v3, v2, 16, 1
	v_add3_u32 v20, v2, v3, s75
	v_or_b32_e32 v2, 1, v172
	v_mov_b32_e32 v3, v173
	v_lshlrev_b64 v[2:3], 11, v[2:3]
	v_lshl_add_u64 v[2:3], v[18:19], 0, v[2:3]
	global_store_short_d16_hi v[2:3], v20, off
	v_mul_f32_e32 v2, 0x3d372713, v4
	v_mul_f32_e32 v2, v4, v2
	v_fma_f32 v2, v4, v2, v4
	v_mul_f32_e32 v2, 0x3fcc422a, v2
	v_mul_f32_e32 v2, 0xbfb8aa3b, v2
	v_exp_f32_e32 v2, v2
	s_nop 0
	v_add_f32_e32 v2, 1.0, v2
	v_rcp_f32_e32 v2, v2
	s_nop 0
	v_mul_f32_e32 v2, v4, v2
	v_bfe_u32 v3, v2, 16, 1
	v_add3_u32 v4, v2, v3, s75
	v_or_b32_e32 v2, 2, v172
	v_mov_b32_e32 v3, v173
	v_lshlrev_b64 v[2:3], 11, v[2:3]
	v_lshl_add_u64 v[2:3], v[18:19], 0, v[2:3]
	global_store_short_d16_hi v[2:3], v4, off
	v_mul_f32_e32 v2, 0x3d372713, v5
	v_mul_f32_e32 v2, v5, v2
	v_fma_f32 v2, v5, v2, v5
	v_mul_f32_e32 v2, 0x3fcc422a, v2
	v_mul_f32_e32 v2, 0xbfb8aa3b, v2
	v_exp_f32_e32 v2, v2
	s_nop 0
	v_add_f32_e32 v2, 1.0, v2
	v_rcp_f32_e32 v2, v2
	s_nop 0
	v_mul_f32_e32 v2, v5, v2
	v_bfe_u32 v3, v2, 16, 1
	v_add3_u32 v4, v2, v3, s75
	v_or_b32_e32 v2, 3, v172
	v_mov_b32_e32 v3, v173
	v_lshlrev_b64 v[2:3], 11, v[2:3]
	v_lshl_add_u64 v[2:3], v[18:19], 0, v[2:3]
	global_store_short_d16_hi v[2:3], v4, off
	v_mul_f32_e32 v2, 0x3d372713, v6
	v_mul_f32_e32 v2, v6, v2
	v_fma_f32 v2, v6, v2, v6
	v_mul_f32_e32 v2, 0x3fcc422a, v2
	v_mul_f32_e32 v2, 0xbfb8aa3b, v2
	v_exp_f32_e32 v2, v2
	s_nop 0
	v_add_f32_e32 v2, 1.0, v2
	v_rcp_f32_e32 v2, v2
	s_nop 0
	v_mul_f32_e32 v2, v6, v2
	v_bfe_u32 v3, v2, 16, 1
	v_add3_u32 v4, v2, v3, s75
	v_or_b32_e32 v2, 8, v172
	v_mov_b32_e32 v3, v173
	v_lshlrev_b64 v[2:3], 11, v[2:3]
	v_lshl_add_u64 v[2:3], v[18:19], 0, v[2:3]
	global_store_short_d16_hi v[2:3], v4, off
	v_mul_f32_e32 v2, 0x3d372713, v7
	v_mul_f32_e32 v2, v7, v2
	v_fma_f32 v2, v7, v2, v7
	v_mul_f32_e32 v2, 0x3fcc422a, v2
	v_mul_f32_e32 v2, 0xbfb8aa3b, v2
	v_exp_f32_e32 v2, v2
	s_nop 0
	v_add_f32_e32 v2, 1.0, v2
	v_rcp_f32_e32 v2, v2
	s_nop 0
	v_mul_f32_e32 v2, v7, v2
	v_bfe_u32 v3, v2, 16, 1
	v_add3_u32 v4, v2, v3, s75
	v_or_b32_e32 v2, 9, v172
	v_mov_b32_e32 v3, v173
	v_lshlrev_b64 v[2:3], 11, v[2:3]
	v_lshl_add_u64 v[2:3], v[18:19], 0, v[2:3]
	global_store_short_d16_hi v[2:3], v4, off
	v_mul_f32_e32 v2, 0x3d372713, v8
	v_mul_f32_e32 v2, v8, v2
	v_fma_f32 v2, v8, v2, v8
	v_mul_f32_e32 v2, 0x3fcc422a, v2
	v_mul_f32_e32 v2, 0xbfb8aa3b, v2
	v_exp_f32_e32 v2, v2
	s_nop 0
	v_add_f32_e32 v2, 1.0, v2
	v_rcp_f32_e32 v2, v2
	s_nop 0
	v_mul_f32_e32 v2, v8, v2
	v_bfe_u32 v3, v2, 16, 1
	v_add3_u32 v4, v2, v3, s75
	v_or_b32_e32 v2, 10, v172
	v_mov_b32_e32 v3, v173
	v_lshlrev_b64 v[2:3], 11, v[2:3]
	v_lshl_add_u64 v[2:3], v[18:19], 0, v[2:3]
	global_store_short_d16_hi v[2:3], v4, off
	v_mul_f32_e32 v2, 0x3d372713, v9
	v_mul_f32_e32 v2, v9, v2
	v_fma_f32 v2, v9, v2, v9
	v_mul_f32_e32 v2, 0x3fcc422a, v2
	v_mul_f32_e32 v2, 0xbfb8aa3b, v2
	v_exp_f32_e32 v2, v2
	s_nop 0
	v_add_f32_e32 v2, 1.0, v2
	v_rcp_f32_e32 v2, v2
	s_nop 0
	v_mul_f32_e32 v2, v9, v2
	v_bfe_u32 v3, v2, 16, 1
	v_add3_u32 v4, v2, v3, s75
	v_or_b32_e32 v2, 11, v172
	v_mov_b32_e32 v3, v173
	v_lshlrev_b64 v[2:3], 11, v[2:3]
	v_lshl_add_u64 v[2:3], v[18:19], 0, v[2:3]
	global_store_short_d16_hi v[2:3], v4, off
	v_mul_f32_e32 v2, 0x3d372713, v10
	v_mul_f32_e32 v2, v10, v2
	v_fma_f32 v2, v10, v2, v10
	v_mul_f32_e32 v2, 0x3fcc422a, v2
	v_mul_f32_e32 v2, 0xbfb8aa3b, v2
	v_exp_f32_e32 v2, v2
	s_nop 0
	v_add_f32_e32 v2, 1.0, v2
	v_rcp_f32_e32 v2, v2
	s_nop 0
	v_mul_f32_e32 v2, v10, v2
	v_bfe_u32 v3, v2, 16, 1
	v_add3_u32 v4, v2, v3, s75
	v_or_b32_e32 v2, 16, v172
	v_mov_b32_e32 v3, v173
	v_lshlrev_b64 v[2:3], 11, v[2:3]
	v_lshl_add_u64 v[2:3], v[18:19], 0, v[2:3]
	global_store_short_d16_hi v[2:3], v4, off
	v_mul_f32_e32 v2, 0x3d372713, v11
	v_mul_f32_e32 v2, v11, v2
	v_fma_f32 v2, v11, v2, v11
	v_mul_f32_e32 v2, 0x3fcc422a, v2
	v_mul_f32_e32 v2, 0xbfb8aa3b, v2
	v_exp_f32_e32 v2, v2
	s_nop 0
	v_add_f32_e32 v2, 1.0, v2
	v_rcp_f32_e32 v2, v2
	s_nop 0
	v_mul_f32_e32 v2, v11, v2
	v_bfe_u32 v3, v2, 16, 1
	v_add3_u32 v4, v2, v3, s75
	v_or_b32_e32 v2, 17, v172
	v_mov_b32_e32 v3, v173
	v_lshlrev_b64 v[2:3], 11, v[2:3]
	v_lshl_add_u64 v[2:3], v[18:19], 0, v[2:3]
	global_store_short_d16_hi v[2:3], v4, off
	v_mul_f32_e32 v2, 0x3d372713, v12
	v_mul_f32_e32 v2, v12, v2
	v_fma_f32 v2, v12, v2, v12
	v_mul_f32_e32 v2, 0x3fcc422a, v2
	v_mul_f32_e32 v2, 0xbfb8aa3b, v2
	v_exp_f32_e32 v2, v2
	s_nop 0
	v_add_f32_e32 v2, 1.0, v2
	v_rcp_f32_e32 v2, v2
	s_nop 0
	v_mul_f32_e32 v2, v12, v2
	v_bfe_u32 v3, v2, 16, 1
	v_add3_u32 v4, v2, v3, s75
	v_or_b32_e32 v2, 18, v172
	v_mov_b32_e32 v3, v173
	v_lshlrev_b64 v[2:3], 11, v[2:3]
	v_lshl_add_u64 v[2:3], v[18:19], 0, v[2:3]
	global_store_short_d16_hi v[2:3], v4, off
	v_mul_f32_e32 v2, 0x3d372713, v13
	v_mul_f32_e32 v2, v13, v2
	v_fma_f32 v2, v13, v2, v13
	v_mul_f32_e32 v2, 0x3fcc422a, v2
	v_mul_f32_e32 v2, 0xbfb8aa3b, v2
	v_exp_f32_e32 v2, v2
	s_nop 0
	v_add_f32_e32 v2, 1.0, v2
	v_rcp_f32_e32 v2, v2
	s_nop 0
	v_mul_f32_e32 v2, v13, v2
	v_bfe_u32 v3, v2, 16, 1
	v_add3_u32 v4, v2, v3, s75
	v_or_b32_e32 v2, 19, v172
	v_mov_b32_e32 v3, v173
	v_lshlrev_b64 v[2:3], 11, v[2:3]
	v_lshl_add_u64 v[2:3], v[18:19], 0, v[2:3]
	global_store_short_d16_hi v[2:3], v4, off
	v_mul_f32_e32 v2, 0x3d372713, v14
	v_mul_f32_e32 v2, v14, v2
	v_fma_f32 v2, v14, v2, v14
	v_mul_f32_e32 v2, 0x3fcc422a, v2
	v_mul_f32_e32 v2, 0xbfb8aa3b, v2
	v_exp_f32_e32 v2, v2
	s_nop 0
	v_add_f32_e32 v2, 1.0, v2
	v_rcp_f32_e32 v2, v2
	s_nop 0
	v_mul_f32_e32 v2, v14, v2
	v_bfe_u32 v3, v2, 16, 1
	v_add3_u32 v4, v2, v3, s75
	v_or_b32_e32 v2, 24, v172
	v_mov_b32_e32 v3, v173
	v_lshlrev_b64 v[2:3], 11, v[2:3]
	v_lshl_add_u64 v[2:3], v[18:19], 0, v[2:3]
	global_store_short_d16_hi v[2:3], v4, off
	v_mul_f32_e32 v2, 0x3d372713, v15
	v_mul_f32_e32 v2, v15, v2
	v_fma_f32 v2, v15, v2, v15
	v_mul_f32_e32 v2, 0x3fcc422a, v2
	v_mul_f32_e32 v2, 0xbfb8aa3b, v2
	v_exp_f32_e32 v2, v2
	s_nop 0
	v_add_f32_e32 v2, 1.0, v2
	v_rcp_f32_e32 v2, v2
	s_nop 0
	v_mul_f32_e32 v2, v15, v2
	v_bfe_u32 v3, v2, 16, 1
	v_add3_u32 v4, v2, v3, s75
	v_or_b32_e32 v2, 25, v172
	v_mov_b32_e32 v3, v173
	v_lshlrev_b64 v[2:3], 11, v[2:3]
	v_lshl_add_u64 v[2:3], v[18:19], 0, v[2:3]
	global_store_short_d16_hi v[2:3], v4, off
	v_mul_f32_e32 v2, 0x3d372713, v16
	v_mul_f32_e32 v2, v16, v2
	v_fma_f32 v2, v16, v2, v16
	v_mul_f32_e32 v2, 0x3fcc422a, v2
	v_mul_f32_e32 v2, 0xbfb8aa3b, v2
	v_exp_f32_e32 v2, v2
	s_nop 0
	v_add_f32_e32 v2, 1.0, v2
	v_rcp_f32_e32 v2, v2
	s_nop 0
	v_mul_f32_e32 v2, v16, v2
	v_bfe_u32 v3, v2, 16, 1
	v_add3_u32 v4, v2, v3, s75
	v_or_b32_e32 v2, 26, v172
	v_mov_b32_e32 v3, v173
	v_lshlrev_b64 v[2:3], 11, v[2:3]
	v_lshl_add_u64 v[2:3], v[18:19], 0, v[2:3]
	global_store_short_d16_hi v[2:3], v4, off
	v_mul_f32_e32 v2, 0x3d372713, v17
	v_mul_f32_e32 v2, v17, v2
	v_fma_f32 v2, v17, v2, v17
	v_mul_f32_e32 v2, 0x3fcc422a, v2
	v_mul_f32_e32 v2, 0xbfb8aa3b, v2
	v_exp_f32_e32 v2, v2
	v_or_b32_e32 v172, 27, v172
	v_add_f32_e32 v2, 1.0, v2
	v_rcp_f32_e32 v2, v2
	s_nop 0
	v_mul_f32_e32 v2, v17, v2
	v_bfe_u32 v3, v2, 16, 1
	v_add3_u32 v4, v2, v3, s75
	v_lshlrev_b64 v[2:3], 11, v[172:173]
	v_lshl_add_u64 v[2:3], v[18:19], 0, v[2:3]
	global_store_short_d16_hi v[2:3], v4, off
	s_branch .LBB0_639
